# speedup vs baseline: 1.0399x; 1.0134x over previous
; #define PG8_STAGE(bufoff, gbase, voff) do { _Pragma("unroll") for (int _i = 0; _i < 2; ++_i) \
;         __builtin_amdgcn_global_load_lds((const unsigned*)((const char*)(gbase) + (voff)[_i]), (PG8_LAS unsigned*)(lds + (bufoff) + ldsw + _i * 8192), 16, 0, 0); } while (0)
; #define PG8_LDA(dst, b, h) do { _Pragma("unroll") for (int m = 0; m < 4; ++m) _Pragma("unroll") for (int k = 0; k < 2; ++k) dst[m][k] = *(const PG8_LAS bf16x8*)(lds + PG8_SA(b, h) + aoff + m * 2048 + k * 1024); } while (0)
; #define PG8_LDB(dst, b, h) do { _Pragma("unroll") for (int n = 0; n < 2; ++n) _Pragma("unroll") for (int k = 0; k < 2; ++k) dst[n][k] = *(const PG8_LAS bf16x8*)(lds + PG8_SB(b, h) + boff + n * 2048 + k * 1024); } while (0)
; #define PG8_MMA(ai, bj, At, Bt) do { __builtin_amdgcn_s_setprio(1); _Pragma("unroll") for (int m = 0; m < 4; ++m) _Pragma("unroll") for (int n = 0; n < 2; ++n) _Pragma("unroll") for (int k = 0; k < 2; ++k) \
;         acc[ai][bj][m][n] = __builtin_amdgcn_mfma_f32_16x16x32_bf16(Bt[n][k], At[m][k], acc[ai][bj][m][n], 0, 0, 0); __builtin_amdgcn_s_setprio(0); } while (0)
; #define PG8_WAIT_V(n) asm volatile("s_waitcnt vmcnt(" #n ")" ::: "memory")
; #define PG8_WAIT_L(n) asm volatile("s_waitcnt lgkmcnt(" #n ")" ::: "memory")
; #define PG8_BAR __builtin_amdgcn_s_barrier()
; #define PG8_SCHED __builtin_amdgcn_sched_barrier(0)
; template <class Epi, class Sched>
; __device__ __forceinline__ void gemm_phase(PG8_LAS unsigned char* lds, const Gemm g, const Sched& S, const Epi& E) {
;     ...
;             PG8_LDB(B0, 0, 0); PG8_SCHED; PG8_LDA(At, 0, 0); PG8_STAGE(PG8_SA(1, 1), a1 + hstep, voffA);
;             PG8_WAIT_L(8); PG8_BAR; PG8_WAIT_L(0); PG8_MMA(0, 0, At, B0); PG8_BAR; PG8_SCHED;
;             PG8_LDB(B1, 0, 1); PG8_STAGE(PG8_SB(0, 0), b2, voffB);
;             PG8_BAR; PG8_WAIT_L(0); PG8_MMA(0, 1, At, B1); PG8_BAR;
;             PG8_LDA(At, 0, 1); PG8_STAGE(PG8_SA(0, 0), a2, voffA);
;             PG8_BAR; PG8_WAIT_L(0); PG8_MMA(1, 0, At, B0); PG8_BAR; PG8_SCHED;
;             PG8_STAGE(PG8_SB(0, 1), b2 + hstep, voffB);
;             PG8_WAIT_V(6); PG8_BAR; PG8_MMA(1, 1, At, B1); PG8_BAR;
.LBB0_144:
	ds_read_b128 v[128:131], v145
	ds_read_b128 v[132:135], v145 offset:1024
	ds_read_b128 v[136:139], v145 offset:2048
	ds_read_b128 v[140:143], v145 offset:3072
	s_add_u32 s20, s18, 0xfff80080
	s_addc_u32 s21, s19, -1
	s_cmp_eq_u32 s59, 28
	s_cselect_b32 s23, s11, s21
	s_cselect_b32 s22, s51, s20
	s_cselect_b32 s21, s9, s58
	s_cselect_b32 s20, s56, s57
	v_lshl_add_u64 v[200:201], s[18:19], 0, v[156:157]
	s_add_i32 m0, s17, 0xc000
	ds_read_b128 v[164:167], v170
	ds_read_b128 v[172:175], v170 offset:1024
	ds_read_b128 v[176:179], v170 offset:2048
	ds_read_b128 v[180:183], v170 offset:3072
	ds_read_b128 v[184:187], v170 offset:4096
	ds_read_b128 v[188:191], v170 offset:5120
	ds_read_b128 v[192:195], v170 offset:6144
	ds_read_b128 v[196:199], v170 offset:7168
	global_load_lds_dwordx4 v[200:201], off
	v_lshl_add_u64 v[200:201], s[18:19], 0, v[158:159]
	s_add_i32 m0, s17, 0xe000
	s_nop 0
	global_load_lds_dwordx4 v[200:201], off
	s_waitcnt lgkmcnt(8)
	s_barrier
	s_waitcnt lgkmcnt(0)
	s_setprio 1
	s_waitcnt lgkmcnt(0)
	v_mfma_f32_16x16x32_bf16 v[124:127], v[128:131], v[164:167], v[124:127]
	v_mfma_f32_16x16x32_bf16 v[120:123], v[136:139], v[164:167], v[120:123]
	v_mfma_f32_16x16x32_bf16 v[116:119], v[128:131], v[176:179], v[116:119]
	v_mfma_f32_16x16x32_bf16 v[112:115], v[136:139], v[176:179], v[112:115]
	v_mfma_f32_16x16x32_bf16 v[108:111], v[128:131], v[184:187], v[108:111]
	v_mfma_f32_16x16x32_bf16 v[100:103], v[136:139], v[184:187], v[100:103]
	v_mfma_f32_16x16x32_bf16 v[92:95], v[128:131], v[192:195], v[92:95]
	v_mfma_f32_16x16x32_bf16 v[80:83], v[136:139], v[192:195], v[80:83]
	v_mfma_f32_16x16x32_bf16 v[124:127], v[132:135], v[172:175], v[124:127]
	v_mfma_f32_16x16x32_bf16 v[120:123], v[140:143], v[172:175], v[120:123]
	v_mfma_f32_16x16x32_bf16 v[116:119], v[132:135], v[180:183], v[116:119]
	v_mfma_f32_16x16x32_bf16 v[112:115], v[140:143], v[180:183], v[112:115]
	v_mfma_f32_16x16x32_bf16 v[108:111], v[132:135], v[188:191], v[108:111]
	v_mfma_f32_16x16x32_bf16 v[100:103], v[140:143], v[188:191], v[100:103]
	v_mfma_f32_16x16x32_bf16 v[92:95], v[132:135], v[196:199], v[92:95]
	v_mfma_f32_16x16x32_bf16 v[80:83], v[140:143], v[196:199], v[80:83]
	s_setprio 0
	s_barrier
	s_add_i32 s30, s48, s27
	v_lshl_add_u64 v[216:217], s[20:21], 0, v[150:151]
	s_mov_b32 m0, s30
	ds_read_b128 v[200:203], v171
	ds_read_b128 v[204:207], v171 offset:1024
	ds_read_b128 v[208:211], v171 offset:2048
	ds_read_b128 v[212:215], v171 offset:3072
	global_load_lds_dwordx4 v[216:217], off
	v_lshl_add_u64 v[218:219], s[20:21], 0, v[154:155]
	s_add_i32 m0, s30, 0x2000
	s_nop 0
	global_load_lds_dwordx4 v[218:219], off
	s_barrier
	s_waitcnt lgkmcnt(0)
	s_setprio 1
	s_waitcnt lgkmcnt(0)
	v_mfma_f32_16x16x32_bf16 v[104:107], v[200:203], v[164:167], v[104:107]
	v_mfma_f32_16x16x32_bf16 v[96:99], v[208:211], v[164:167], v[96:99]
	v_mfma_f32_16x16x32_bf16 v[88:91], v[200:203], v[176:179], v[88:91]
	v_mfma_f32_16x16x32_bf16 v[84:87], v[208:211], v[176:179], v[84:87]
	v_mfma_f32_16x16x32_bf16 v[76:79], v[200:203], v[184:187], v[76:79]
	v_mfma_f32_16x16x32_bf16 v[72:75], v[208:211], v[184:187], v[72:75]
	v_mfma_f32_16x16x32_bf16 v[68:71], v[200:203], v[192:195], v[68:71]
	v_mfma_f32_16x16x32_bf16 v[64:67], v[208:211], v[192:195], v[64:67]
	v_mfma_f32_16x16x32_bf16 v[104:107], v[204:207], v[172:175], v[104:107]
	v_mfma_f32_16x16x32_bf16 v[96:99], v[212:215], v[172:175], v[96:99]
	v_mfma_f32_16x16x32_bf16 v[88:91], v[204:207], v[180:183], v[88:91]
	v_mfma_f32_16x16x32_bf16 v[84:87], v[212:215], v[180:183], v[84:87]
	v_mfma_f32_16x16x32_bf16 v[76:79], v[204:207], v[188:191], v[76:79]
	v_mfma_f32_16x16x32_bf16 v[72:75], v[212:215], v[188:191], v[72:75]
	v_mfma_f32_16x16x32_bf16 v[68:71], v[204:207], v[196:199], v[68:71]
	v_mfma_f32_16x16x32_bf16 v[64:67], v[212:215], v[196:199], v[64:67]
	s_setprio 0
	s_mov_b32 m0, s17
	v_lshl_add_u64 v[220:221], s[22:23], 0, v[148:149]
	s_barrier
	ds_read_b128 v[164:167], v170 offset:16384
	ds_read_b128 v[172:175], v170 offset:17408
	ds_read_b128 v[176:179], v170 offset:18432
	ds_read_b128 v[180:183], v170 offset:19456
	ds_read_b128 v[184:187], v170 offset:20480
	ds_read_b128 v[188:191], v170 offset:21504
	ds_read_b128 v[192:195], v170 offset:22528
	ds_read_b128 v[196:199], v170 offset:23552
	global_load_lds_dwordx4 v[220:221], off
	v_lshl_add_u64 v[222:223], s[22:23], 0, v[152:153]
	s_mov_b32 m0, s40
	s_nop 0
	global_load_lds_dwordx4 v[222:223], off
	s_barrier
	s_waitcnt lgkmcnt(0)
	s_setprio 1
	s_waitcnt lgkmcnt(0)
	v_mfma_f32_16x16x32_bf16 v[60:63], v[128:131], v[164:167], v[60:63]
	v_mfma_f32_16x16x32_bf16 v[56:59], v[136:139], v[164:167], v[56:59]
	v_mfma_f32_16x16x32_bf16 v[48:51], v[128:131], v[176:179], v[48:51]
	v_mfma_f32_16x16x32_bf16 v[40:43], v[136:139], v[176:179], v[40:43]
	v_mfma_f32_16x16x32_bf16 v[32:35], v[128:131], v[184:187], v[32:35]
	v_mfma_f32_16x16x32_bf16 v[24:27], v[136:139], v[184:187], v[24:27]
	v_mfma_f32_16x16x32_bf16 v[16:19], v[128:131], v[192:195], v[16:19]
	v_mfma_f32_16x16x32_bf16 v[8:11], v[136:139], v[192:195], v[8:11]
	v_mfma_f32_16x16x32_bf16 v[60:63], v[132:135], v[172:175], v[60:63]
	v_mfma_f32_16x16x32_bf16 v[56:59], v[140:143], v[172:175], v[56:59]
	v_mfma_f32_16x16x32_bf16 v[48:51], v[132:135], v[180:183], v[48:51]
	v_mfma_f32_16x16x32_bf16 v[40:43], v[140:143], v[180:183], v[40:43]
	v_mfma_f32_16x16x32_bf16 v[32:35], v[132:135], v[188:191], v[32:35]
	v_mfma_f32_16x16x32_bf16 v[24:27], v[140:143], v[188:191], v[24:27]
	v_mfma_f32_16x16x32_bf16 v[16:19], v[132:135], v[196:199], v[16:19]
	v_mfma_f32_16x16x32_bf16 v[8:11], v[140:143], v[196:199], v[8:11]
	s_setprio 0
	s_barrier
; #define PG8_STAGE(bufoff, gbase, voff) do { _Pragma("unroll") for (int _i = 0; _i < 2; ++_i) \
;         __builtin_amdgcn_global_load_lds((const unsigned*)((const char*)(gbase) + (voff)[_i]), (PG8_LAS unsigned*)(lds + (bufoff) + ldsw + _i * 8192), 16, 0, 0); } while (0)
; #define PG8_LDA(dst, b, h) do { _Pragma("unroll") for (int m = 0; m < 4; ++m) _Pragma("unroll") for (int k = 0; k < 2; ++k) dst[m][k] = *(const PG8_LAS bf16x8*)(lds + PG8_SA(b, h) + aoff + m * 2048 + k * 1024); } while (0)
; #define PG8_LDB(dst, b, h) do { _Pragma("unroll") for (int n = 0; n < 2; ++n) _Pragma("unroll") for (int k = 0; k < 2; ++k) dst[n][k] = *(const PG8_LAS bf16x8*)(lds + PG8_SB(b, h) + boff + n * 2048 + k * 1024); } while (0)
; #define PG8_MMA(ai, bj, At, Bt) do { __builtin_amdgcn_s_setprio(1); _Pragma("unroll") for (int m = 0; m < 4; ++m) _Pragma("unroll") for (int n = 0; n < 2; ++n) _Pragma("unroll") for (int k = 0; k < 2; ++k) \
;         acc[ai][bj][m][n] = __builtin_amdgcn_mfma_f32_16x16x32_bf16(Bt[n][k], At[m][k], acc[ai][bj][m][n], 0, 0, 0); __builtin_amdgcn_s_setprio(0); } while (0)
; #define PG8_WAIT_V(n) asm volatile("s_waitcnt vmcnt(" #n ")" ::: "memory")
; #define PG8_WAIT_L(n) asm volatile("s_waitcnt lgkmcnt(" #n ")" ::: "memory")
; #define PG8_BAR __builtin_amdgcn_s_barrier()
; #define PG8_SCHED __builtin_amdgcn_sched_barrier(0)
; template <class Epi, class Sched>
; __device__ __forceinline__ void gemm_phase(PG8_LAS unsigned char* lds, const Gemm g, const Sched& S, const Epi& E) {
;     ...
;             PG8_STAGE(PG8_SB(0, 1), b2 + hstep, voffB);
;             PG8_WAIT_V(6); PG8_BAR; PG8_MMA(1, 1, At, B1); PG8_BAR;
;             PG8_LDB(B0, 1, 0); PG8_SCHED; PG8_LDA(At, 1, 0); PG8_STAGE(PG8_SA(0, 1), a2 + hstep, voffA);
;             PG8_WAIT_L(8); PG8_BAR; PG8_WAIT_L(0); PG8_MMA(0, 0, At, B0); PG8_BAR; PG8_SCHED;
;             PG8_LDB(B1, 1, 1); PG8_STAGE(PG8_SB(1, 0), b3, voffB);
;             PG8_BAR; PG8_WAIT_L(0); PG8_MMA(0, 1, At, B1); PG8_BAR;
;             PG8_LDA(At, 1, 1); PG8_STAGE(PG8_SA(1, 0), a3, voffA);
	s_add_u32 s60, s20, 0x80000
	s_addc_u32 s61, s21, 0
	s_add_i32 s30, s49, s27
	v_lshl_add_u64 v[128:129], s[60:61], 0, v[150:151]
	s_mov_b32 m0, s30
	s_nop 0
	global_load_lds_dwordx4 v[128:129], off
	v_lshl_add_u64 v[128:129], s[60:61], 0, v[154:155]
	s_add_i32 m0, s30, 0x2000
	s_nop 0
	global_load_lds_dwordx4 v[128:129], off
	s_waitcnt vmcnt(6)
	s_barrier
	s_setprio 1
	v_mfma_f32_16x16x32_bf16 v[52:55], v[200:203], v[164:167], v[52:55]
	v_mfma_f32_16x16x32_bf16 v[44:47], v[208:211], v[164:167], v[44:47]
	v_mfma_f32_16x16x32_bf16 v[36:39], v[200:203], v[176:179], v[36:39]
	v_mfma_f32_16x16x32_bf16 v[28:31], v[208:211], v[176:179], v[28:31]
	v_mfma_f32_16x16x32_bf16 v[20:23], v[200:203], v[184:187], v[20:23]
	v_mfma_f32_16x16x32_bf16 v[12:15], v[208:211], v[184:187], v[12:15]
	v_mfma_f32_16x16x32_bf16 v[4:7], v[200:203], v[192:195], v[4:7]
	v_mfma_f32_16x16x32_bf16 v[0:3], v[208:211], v[192:195], v[0:3]
	v_mfma_f32_16x16x32_bf16 v[52:55], v[204:207], v[172:175], v[52:55]
	v_mfma_f32_16x16x32_bf16 v[44:47], v[212:215], v[172:175], v[44:47]
	v_mfma_f32_16x16x32_bf16 v[36:39], v[204:207], v[180:183], v[36:39]
	v_mfma_f32_16x16x32_bf16 v[28:31], v[212:215], v[180:183], v[28:31]
	v_mfma_f32_16x16x32_bf16 v[20:23], v[204:207], v[188:191], v[20:23]
	v_mfma_f32_16x16x32_bf16 v[12:15], v[212:215], v[188:191], v[12:15]
	v_mfma_f32_16x16x32_bf16 v[4:7], v[204:207], v[196:199], v[4:7]
	v_mfma_f32_16x16x32_bf16 v[0:3], v[212:215], v[196:199], v[0:3]
	s_setprio 0
	s_add_i32 s30, 0, 0x18000
	v_add_u32_e32 v140, s30, v147
	s_barrier
	ds_read_b128 v[128:131], v140
	ds_read_b128 v[132:135], v140 offset:1024
	ds_read_b128 v[136:139], v140 offset:2048
	ds_read_b128 v[140:143], v140 offset:3072
	s_add_u32 s22, s22, 0x80000
	s_addc_u32 s23, s23, 0
	s_mov_b32 m0, s41
	v_lshl_add_u64 v[200:201], s[22:23], 0, v[148:149]
	ds_read_b128 v[164:167], v170 offset:32768
	ds_read_b128 v[172:175], v170 offset:33792
	ds_read_b128 v[176:179], v170 offset:34816
	ds_read_b128 v[180:183], v170 offset:35840
	ds_read_b128 v[184:187], v170 offset:36864
	ds_read_b128 v[188:191], v170 offset:37888
	ds_read_b128 v[192:195], v170 offset:38912
	ds_read_b128 v[196:199], v170 offset:39936
	global_load_lds_dwordx4 v[200:201], off
	v_lshl_add_u64 v[200:201], s[22:23], 0, v[152:153]
	s_mov_b32 m0, s42
	s_nop 0
	global_load_lds_dwordx4 v[200:201], off
	s_waitcnt lgkmcnt(8)
	s_barrier
	s_waitcnt lgkmcnt(0)
	s_setprio 1
	s_waitcnt lgkmcnt(0)
	v_mfma_f32_16x16x32_bf16 v[124:127], v[128:131], v[164:167], v[124:127]
	v_mfma_f32_16x16x32_bf16 v[120:123], v[136:139], v[164:167], v[120:123]
	v_mfma_f32_16x16x32_bf16 v[116:119], v[128:131], v[176:179], v[116:119]
	v_mfma_f32_16x16x32_bf16 v[112:115], v[136:139], v[176:179], v[112:115]
	v_mfma_f32_16x16x32_bf16 v[108:111], v[128:131], v[184:187], v[108:111]
	v_mfma_f32_16x16x32_bf16 v[100:103], v[136:139], v[184:187], v[100:103]
	v_mfma_f32_16x16x32_bf16 v[92:95], v[128:131], v[192:195], v[92:95]
	v_mfma_f32_16x16x32_bf16 v[80:83], v[136:139], v[192:195], v[80:83]
	v_mfma_f32_16x16x32_bf16 v[124:127], v[132:135], v[172:175], v[124:127]
	v_mfma_f32_16x16x32_bf16 v[120:123], v[140:143], v[172:175], v[120:123]
	v_mfma_f32_16x16x32_bf16 v[116:119], v[132:135], v[180:183], v[116:119]
	v_mfma_f32_16x16x32_bf16 v[112:115], v[140:143], v[180:183], v[112:115]
	v_mfma_f32_16x16x32_bf16 v[108:111], v[132:135], v[188:191], v[108:111]
	v_mfma_f32_16x16x32_bf16 v[100:103], v[140:143], v[188:191], v[100:103]
	v_mfma_f32_16x16x32_bf16 v[92:95], v[132:135], v[196:199], v[92:95]
	v_mfma_f32_16x16x32_bf16 v[80:83], v[140:143], v[196:199], v[80:83]
	s_setprio 0
	s_barrier
	s_add_i32 s22, 0, 0x1c000
	s_add_i32 s23, s30, s27
	v_add_u32_e32 v212, s22, v147
	v_lshl_add_u64 v[216:217], v[216:217], 0, s[6:7]
	s_mov_b32 m0, s23
	ds_read_b128 v[200:203], v212
	ds_read_b128 v[204:207], v212 offset:1024
	ds_read_b128 v[208:211], v212 offset:2048
	ds_read_b128 v[212:215], v212 offset:3072
	global_load_lds_dwordx4 v[216:217], off
	v_lshl_add_u64 v[216:217], v[218:219], 0, s[6:7]
	s_add_i32 m0, s23, 0x2000
	s_nop 0
	global_load_lds_dwordx4 v[216:217], off
	s_barrier
	s_waitcnt lgkmcnt(0)
	s_setprio 1
	s_waitcnt lgkmcnt(0)
	v_mfma_f32_16x16x32_bf16 v[104:107], v[200:203], v[164:167], v[104:107]
	v_mfma_f32_16x16x32_bf16 v[96:99], v[208:211], v[164:167], v[96:99]
	v_mfma_f32_16x16x32_bf16 v[88:91], v[200:203], v[176:179], v[88:91]
	v_mfma_f32_16x16x32_bf16 v[84:87], v[208:211], v[176:179], v[84:87]
	v_mfma_f32_16x16x32_bf16 v[76:79], v[200:203], v[184:187], v[76:79]
	v_mfma_f32_16x16x32_bf16 v[72:75], v[208:211], v[184:187], v[72:75]
	v_mfma_f32_16x16x32_bf16 v[68:71], v[200:203], v[192:195], v[68:71]
	v_mfma_f32_16x16x32_bf16 v[64:67], v[208:211], v[192:195], v[64:67]
	v_mfma_f32_16x16x32_bf16 v[104:107], v[204:207], v[172:175], v[104:107]
	v_mfma_f32_16x16x32_bf16 v[96:99], v[212:215], v[172:175], v[96:99]
	v_mfma_f32_16x16x32_bf16 v[88:91], v[204:207], v[180:183], v[88:91]
	v_mfma_f32_16x16x32_bf16 v[84:87], v[212:215], v[180:183], v[84:87]
	v_mfma_f32_16x16x32_bf16 v[76:79], v[204:207], v[188:191], v[76:79]
	v_mfma_f32_16x16x32_bf16 v[72:75], v[212:215], v[188:191], v[72:75]
	v_mfma_f32_16x16x32_bf16 v[68:71], v[204:207], v[196:199], v[68:71]
	v_mfma_f32_16x16x32_bf16 v[64:67], v[212:215], v[196:199], v[64:67]
	s_setprio 0
	s_mov_b32 m0, s44
	v_lshl_add_u64 v[216:217], v[220:221], 0, s[6:7]
	s_barrier
	ds_read_b128 v[164:167], v170 offset:49152
	ds_read_b128 v[172:175], v170 offset:50176
	ds_read_b128 v[176:179], v170 offset:51200
	ds_read_b128 v[180:183], v170 offset:52224
	ds_read_b128 v[184:187], v170 offset:53248
	ds_read_b128 v[188:191], v170 offset:54272
	ds_read_b128 v[192:195], v170 offset:55296
	ds_read_b128 v[196:199], v170 offset:56320
	global_load_lds_dwordx4 v[216:217], off
	v_lshl_add_u64 v[216:217], v[222:223], 0, s[6:7]
	s_mov_b32 m0, s45
	s_nop 0
	global_load_lds_dwordx4 v[216:217], off
	s_barrier
; #define PG8_STAGE(bufoff, gbase, voff) do { _Pragma("unroll") for (int _i = 0; _i < 2; ++_i) \
;         __builtin_amdgcn_global_load_lds((const unsigned*)((const char*)(gbase) + (voff)[_i]), (PG8_LAS unsigned*)(lds + (bufoff) + ldsw + _i * 8192), 16, 0, 0); } while (0)
; #define PG8_MMA(ai, bj, At, Bt) do { __builtin_amdgcn_s_setprio(1); _Pragma("unroll") for (int m = 0; m < 4; ++m) _Pragma("unroll") for (int n = 0; n < 2; ++n) _Pragma("unroll") for (int k = 0; k < 2; ++k) \
;         acc[ai][bj][m][n] = __builtin_amdgcn_mfma_f32_16x16x32_bf16(Bt[n][k], At[m][k], acc[ai][bj][m][n], 0, 0, 0); __builtin_amdgcn_s_setprio(0); } while (0)
; #define PG8_WAIT_V(n) asm volatile("s_waitcnt vmcnt(" #n ")" ::: "memory")
; #define PG8_WAIT_L(n) asm volatile("s_waitcnt lgkmcnt(" #n ")" ::: "memory")
; #define PG8_BAR __builtin_amdgcn_s_barrier()
; #define PG8_SCHED __builtin_amdgcn_sched_barrier(0)
; template <class Epi, class Sched>
; __device__ __forceinline__ void gemm_phase(PG8_LAS unsigned char* lds, const Gemm g, const Sched& S, const Epi& E) {
;     ...
;             PG8_BAR; PG8_WAIT_L(0); PG8_MMA(1, 0, At, B0); PG8_BAR; PG8_SCHED;
;             PG8_STAGE(PG8_SB(1, 1), b3 + hstep, voffB);
;             PG8_WAIT_V(6); PG8_BAR; PG8_MMA(1, 1, At, B1); PG8_BAR;
;     __device__ __forceinline__ void operator()(AccRef acc, const Unit& u, int wr, int wc, int fr, int fq) const {
;         const int c0 = u.pn * 256 + wc * 32 + 8 * fq;
;         f32x4 sc[2][2];
; #pragma unroll
;         for (int bj = 0; bj < 2; ++bj)
; #pragma unroll
;             for (int n = 0; n < 2; ++n) sc[bj][n] = *(const f32x4*)(rinv + c0 + bj * 128 + n * 4);
; #pragma unroll
;         for (int ai = 0; ai < 2; ++ai)
; #pragma unroll
;             for (int m = 0; m < 4; ++m) {
;                 const int r = u.pm * 256 + ai * 128 + wr * 64 + m * 16 + fr;
;                 bf16_t* rowp = O + (size_t)r * T + c0;
	s_waitcnt lgkmcnt(0)
	s_setprio 1
	s_waitcnt lgkmcnt(0)
	v_mfma_f32_16x16x32_bf16 v[60:63], v[128:131], v[164:167], v[60:63]
	v_mfma_f32_16x16x32_bf16 v[56:59], v[136:139], v[164:167], v[56:59]
	v_mfma_f32_16x16x32_bf16 v[48:51], v[128:131], v[176:179], v[48:51]
	v_mfma_f32_16x16x32_bf16 v[40:43], v[136:139], v[176:179], v[40:43]
	v_mfma_f32_16x16x32_bf16 v[32:35], v[128:131], v[184:187], v[32:35]
	v_mfma_f32_16x16x32_bf16 v[24:27], v[136:139], v[184:187], v[24:27]
	v_mfma_f32_16x16x32_bf16 v[16:19], v[128:131], v[192:195], v[16:19]
	v_mfma_f32_16x16x32_bf16 v[8:11], v[136:139], v[192:195], v[8:11]
	v_mfma_f32_16x16x32_bf16 v[60:63], v[132:135], v[172:175], v[60:63]
	v_mfma_f32_16x16x32_bf16 v[56:59], v[140:143], v[172:175], v[56:59]
	v_mfma_f32_16x16x32_bf16 v[48:51], v[132:135], v[180:183], v[48:51]
	v_mfma_f32_16x16x32_bf16 v[40:43], v[140:143], v[180:183], v[40:43]
	v_mfma_f32_16x16x32_bf16 v[32:35], v[132:135], v[188:191], v[32:35]
	v_mfma_f32_16x16x32_bf16 v[24:27], v[140:143], v[188:191], v[24:27]
	v_mfma_f32_16x16x32_bf16 v[16:19], v[132:135], v[196:199], v[16:19]
	v_mfma_f32_16x16x32_bf16 v[8:11], v[140:143], v[196:199], v[8:11]
	s_setprio 0
	s_barrier
	s_add_u32 s20, s20, 0x80080
	s_addc_u32 s21, s21, 0
	s_add_i32 s22, s22, s27
	v_lshl_add_u64 v[128:129], s[20:21], 0, v[150:151]
	s_mov_b32 m0, s22
	s_nop 0
	global_load_lds_dwordx4 v[128:129], off
	v_lshl_add_u64 v[128:129], s[20:21], 0, v[154:155]
	s_add_i32 m0, s22, 0x2000
	s_nop 0
	global_load_lds_dwordx4 v[128:129], off
	s_waitcnt vmcnt(6)
	s_barrier
	s_setprio 1
	v_mfma_f32_16x16x32_bf16 v[52:55], v[200:203], v[164:167], v[52:55]
	v_mfma_f32_16x16x32_bf16 v[44:47], v[208:211], v[164:167], v[44:47]
	v_mfma_f32_16x16x32_bf16 v[36:39], v[200:203], v[176:179], v[36:39]
	v_mfma_f32_16x16x32_bf16 v[28:31], v[208:211], v[176:179], v[28:31]
	v_mfma_f32_16x16x32_bf16 v[20:23], v[200:203], v[184:187], v[20:23]
	v_mfma_f32_16x16x32_bf16 v[12:15], v[208:211], v[184:187], v[12:15]
	v_mfma_f32_16x16x32_bf16 v[4:7], v[200:203], v[192:195], v[4:7]
	v_mfma_f32_16x16x32_bf16 v[0:3], v[208:211], v[192:195], v[0:3]
	v_mfma_f32_16x16x32_bf16 v[52:55], v[204:207], v[172:175], v[52:55]
	v_mfma_f32_16x16x32_bf16 v[44:47], v[212:215], v[172:175], v[44:47]
	v_mfma_f32_16x16x32_bf16 v[36:39], v[204:207], v[180:183], v[36:39]
	v_mfma_f32_16x16x32_bf16 v[28:31], v[212:215], v[180:183], v[28:31]
	v_mfma_f32_16x16x32_bf16 v[20:23], v[204:207], v[188:191], v[20:23]
	v_mfma_f32_16x16x32_bf16 v[12:15], v[212:215], v[188:191], v[12:15]
	v_mfma_f32_16x16x32_bf16 v[4:7], v[204:207], v[196:199], v[4:7]
	v_mfma_f32_16x16x32_bf16 v[0:3], v[212:215], v[196:199], v[0:3]
	s_setprio 0
	s_add_i32 s59, s59, 2
	s_add_u32 s18, s18, 0x100
	s_addc_u32 s19, s19, 0
	s_add_u32 s57, s57, 0x100
	s_addc_u32 s58, s58, 0
	s_cmp_gt_u32 s59, 29
	s_barrier
	s_cbranch_scc0 .LBB0_144
	v_lshl_or_b32 v166, s50, 8, v169
	v_mov_b32_e32 v244, 0x50000
	v_mov_b32_e32 v245, 0
	v_ashrrev_i32_e32 v167, 31, v166
	v_lshl_add_u64 v[128:129], v[166:167], 2, s[28:29]
	global_load_dwordx4 v[140:143], v[128:129], off
	global_load_dwordx4 v[136:139], v[128:129], off offset:16
	global_load_dwordx4 v[132:135], v[128:129], off offset:512
	s_nop 0
	global_load_dwordx4 v[128:131], v[128:129], off offset:528
	v_lshl_add_u32 v164, s16, 8, v168
	v_ashrrev_i32_e32 v165, 31, v164
	v_or_b32_e32 v172, 16, v164
	v_lshlrev_b64 v[178:179], 4, v[164:165]
	v_mul_u32_u24_e32 v166, 0xa00, v166
	v_ashrrev_i32_e32 v173, 31, v172
	v_lshl_add_u64 v[178:179], s[0:1], 0, v[178:179]
	v_or_b32_e32 v174, 32, v164
	v_lshlrev_b64 v[172:173], 4, v[172:173]
	v_lshl_add_u64 v[178:179], v[178:179], 0, v[166:167]
	v_ashrrev_i32_e32 v175, 31, v174
	v_lshl_add_u64 v[172:173], s[0:1], 0, v[172:173]
	v_or_b32_e32 v176, 48, v164
	v_lshlrev_b64 v[174:175], 4, v[174:175]
	v_lshl_add_u64 v[172:173], v[172:173], 0, v[166:167]
	v_ashrrev_i32_e32 v177, 31, v176
	v_lshl_add_u64 v[174:175], s[0:1], 0, v[174:175]
	v_lshlrev_b64 v[176:177], 4, v[176:177]
	v_lshl_add_u64 v[174:175], v[174:175], 0, v[166:167]
	v_lshl_add_u64 v[176:177], s[0:1], 0, v[176:177]
	v_lshl_add_u64 v[176:177], v[176:177], 0, v[166:167]
	s_and_b64 vcc, exec, s[4:5]
	s_mov_b32 s50, s8
	s_mov_b32 s16, s10
	s_mov_b64 s[20:21], s[14:15]
	s_mov_b64 s[18:19], s[12:13]
	s_waitcnt vmcnt(0)
; __device__ __forceinline__ uint4 pk8(f32x4 a, f32x4 b) { return make_uint4(cvt_pk_bf16(a[0], a[1]), cvt_pk_bf16(a[2], a[3]), cvt_pk_bf16(b[0], b[1]), cvt_pk_bf16(b[2], b[3])); }
;     __device__ __forceinline__ void operator()(AccRef acc, const Unit& u, int wr, int wc, int fr, int fq) const {
;     ...
; #pragma unroll
;         for (int ai = 0; ai < 2; ++ai)
; #pragma unroll
;             for (int m = 0; m < 4; ++m) {
;                 const int r = u.pm * 256 + ai * 128 + wr * 64 + m * 16 + fr;
;                 bf16_t* rowp = O + (size_t)r * T + c0;
; #pragma unroll
;                 for (int bj = 0; bj < 2; ++bj) *(uint4*)(rowp + bj * 128) = pk8(acc[ai][bj][m][0] * sc[bj][0], acc[ai][bj][m][1] * sc[bj][1]);
;             }
	v_pk_mul_f32 v[126:127], v[126:127], v[142:143]
	v_pk_mul_f32 v[124:125], v[124:125], v[140:141]
	v_pk_mul_f32 v[182:183], v[70:71], v[134:135]
	v_cvt_pk_bf16_f32 v70, v124, v125
	v_cvt_pk_bf16_f32 v71, v126, v127
	v_pk_mul_f32 v[122:123], v[122:123], v[138:139]
	v_pk_mul_f32 v[120:121], v[120:121], v[136:137]
	v_pk_mul_f32 v[106:107], v[106:107], v[134:135]
	v_pk_mul_f32 v[104:105], v[104:105], v[132:133]
	v_pk_mul_f32 v[180:181], v[72:73], v[128:129]
	v_cvt_pk_bf16_f32 v72, v120, v121
	v_cvt_pk_bf16_f32 v73, v122, v123
	global_store_dwordx4 v[178:179], v[70:73], off
	v_pk_mul_f32 v[98:99], v[98:99], v[130:131]
	v_pk_mul_f32 v[96:97], v[96:97], v[128:129]
	v_cvt_pk_bf16_f32 v70, v104, v105
	v_cvt_pk_bf16_f32 v71, v106, v107
	v_pk_mul_f32 v[118:119], v[118:119], v[142:143]
	v_pk_mul_f32 v[116:117], v[116:117], v[140:141]
	v_cvt_pk_bf16_f32 v72, v96, v97
	v_cvt_pk_bf16_f32 v73, v98, v99
	v_lshl_add_u64 v[246:247], v[178:179], 0, v[244:245]
	global_store_dwordx4 v[246:247], v[70:73], off
	v_pk_mul_f32 v[114:115], v[114:115], v[138:139]
	v_pk_mul_f32 v[112:113], v[112:113], v[136:137]
	v_cvt_pk_bf16_f32 v70, v116, v117
	v_cvt_pk_bf16_f32 v71, v118, v119
	v_pk_mul_f32 v[90:91], v[90:91], v[134:135]
	v_pk_mul_f32 v[88:89], v[88:89], v[132:133]
	v_cvt_pk_bf16_f32 v72, v112, v113
	v_cvt_pk_bf16_f32 v73, v114, v115
	global_store_dwordx4 v[172:173], v[70:73], off
	v_pk_mul_f32 v[86:87], v[86:87], v[130:131]
	v_pk_mul_f32 v[84:85], v[84:85], v[128:129]
	v_cvt_pk_bf16_f32 v70, v88, v89
	v_cvt_pk_bf16_f32 v71, v90, v91
	v_pk_mul_f32 v[110:111], v[110:111], v[142:143]
	v_pk_mul_f32 v[108:109], v[108:109], v[140:141]
	v_cvt_pk_bf16_f32 v72, v84, v85
	v_cvt_pk_bf16_f32 v73, v86, v87
	v_lshl_add_u64 v[246:247], v[172:173], 0, v[244:245]
	global_store_dwordx4 v[246:247], v[70:73], off
	v_pk_mul_f32 v[102:103], v[102:103], v[138:139]
	v_pk_mul_f32 v[100:101], v[100:101], v[136:137]
	v_cvt_pk_bf16_f32 v70, v108, v109
	v_cvt_pk_bf16_f32 v71, v110, v111
	v_pk_mul_f32 v[78:79], v[78:79], v[134:135]
	v_pk_mul_f32 v[76:77], v[76:77], v[132:133]
	v_cvt_pk_bf16_f32 v72, v100, v101
	v_cvt_pk_bf16_f32 v73, v102, v103
	global_store_dwordx4 v[174:175], v[70:73], off
	v_pk_mul_f32 v[74:75], v[74:75], v[130:131]
	v_pk_mul_f32 v[94:95], v[94:95], v[142:143]
	v_cvt_pk_bf16_f32 v70, v76, v77
	v_cvt_pk_bf16_f32 v71, v78, v79
	v_pk_mul_f32 v[92:93], v[92:93], v[140:141]
	v_cvt_pk_bf16_f32 v72, v180, v181
	v_cvt_pk_bf16_f32 v73, v74, v75
	v_lshl_add_u64 v[246:247], v[174:175], 0, v[244:245]
	global_store_dwordx4 v[246:247], v[70:73], off
	v_pk_mul_f32 v[82:83], v[82:83], v[138:139]
	v_pk_mul_f32 v[80:81], v[80:81], v[136:137]
	v_cvt_pk_bf16_f32 v70, v92, v93
	v_cvt_pk_bf16_f32 v71, v94, v95
	v_pk_mul_f32 v[68:69], v[68:69], v[132:133]
	v_cvt_pk_bf16_f32 v72, v80, v81
	v_cvt_pk_bf16_f32 v73, v82, v83
	global_store_dwordx4 v[176:177], v[70:73], off
	v_pk_mul_f32 v[62:63], v[62:63], v[142:143]
	v_pk_mul_f32 v[60:61], v[60:61], v[140:141]
	v_pk_mul_f32 v[70:71], v[66:67], v[130:131]
	v_pk_mul_f32 v[66:67], v[64:65], v[128:129]
	v_cvt_pk_bf16_f32 v64, v68, v69
	v_cvt_pk_bf16_f32 v65, v182, v183
	v_pk_mul_f32 v[52:53], v[52:53], v[132:133]
	v_cvt_pk_bf16_f32 v66, v66, v67
	v_cvt_pk_bf16_f32 v67, v70, v71
	v_lshl_add_u64 v[246:247], v[176:177], 0, v[244:245]
	global_store_dwordx4 v[246:247], v[64:67], off
	v_pk_mul_f32 v[54:55], v[54:55], v[134:135]
	v_pk_mul_f32 v[48:49], v[48:49], v[140:141]
	v_add_u32_e32 v64, 0x80, v164
	v_ashrrev_i32_e32 v65, 31, v64
	v_lshlrev_b64 v[64:65], 4, v[64:65]
	v_lshl_add_u64 v[64:65], s[0:1], 0, v[64:65]
	v_lshl_add_u64 v[64:65], v[64:65], 0, v[166:167]
; #define PG8_WAIT_V(n) asm volatile("s_waitcnt vmcnt(" #n ")" ::: "memory")
; #define PG8_BAR __builtin_amdgcn_s_barrier()
; __device__ __forceinline__ uint4 pk8(f32x4 a, f32x4 b) { return make_uint4(cvt_pk_bf16(a[0], a[1]), cvt_pk_bf16(a[2], a[3]), cvt_pk_bf16(b[0], b[1]), cvt_pk_bf16(b[2], b[3])); }
; template <class Epi, class Sched>
; __device__ __forceinline__ void gemm_phase(PG8_LAS unsigned char* lds, const Gemm g, const Sched& S, const Epi& E) {
;     ...
;         if constexpr (!Epi::AFTER_DRAIN) { E(acc, cur, wr, wc, fr, fq); S.done(cur); }
;         if (!has_next) break;
; #pragma unroll
;         for (int a = 0; a < 2; ++a)
; #pragma unroll
;             for (int b = 0; b < 2; ++b)
; #pragma unroll
;                 for (int m = 0; m < 4; ++m)
; #pragma unroll
;                     for (int n = 0; n < 2; ++n) acc[a][b][m][n] = (f32x4){0.f, 0.f, 0.f, 0.f};
;         cur = nxt; cA = nA; cB = nB; ++ui;
;     }
;     PG8_WAIT_V(0);
;     if (wr == 0) PG8_BAR;
;     PG8_BAR;
;     __device__ __forceinline__ void operator()(AccRef acc, const Unit& u, int wr, int wc, int fr, int fq) const {
;     ...
; #pragma unroll
;         for (int ai = 0; ai < 2; ++ai)
; #pragma unroll
;             for (int m = 0; m < 4; ++m) {
;                 const int r = u.pm * 256 + ai * 128 + wr * 64 + m * 16 + fr;
;                 bf16_t* rowp = O + (size_t)r * T + c0;
; #pragma unroll
;                 for (int bj = 0; bj < 2; ++bj) *(uint4*)(rowp + bj * 128) = pk8(acc[ai][bj][m][0] * sc[bj][0], acc[ai][bj][m][1] * sc[bj][1]);
;             }
	v_pk_mul_f32 v[66:67], v[58:59], v[138:139]
	v_pk_mul_f32 v[58:59], v[56:57], v[136:137]
	v_cvt_pk_bf16_f32 v56, v60, v61
	v_cvt_pk_bf16_f32 v57, v62, v63
	v_pk_mul_f32 v[36:37], v[36:37], v[132:133]
	v_cvt_pk_bf16_f32 v58, v58, v59
	v_cvt_pk_bf16_f32 v59, v66, v67
	global_store_dwordx4 v[64:65], v[56:59], off
	v_pk_mul_f32 v[38:39], v[38:39], v[134:135]
	v_pk_mul_f32 v[32:33], v[32:33], v[140:141]
	v_pk_mul_f32 v[56:57], v[46:47], v[130:131]
	v_pk_mul_f32 v[46:47], v[44:45], v[128:129]
	v_cvt_pk_bf16_f32 v44, v52, v53
	v_cvt_pk_bf16_f32 v45, v54, v55
	v_pk_mul_f32 v[20:21], v[20:21], v[132:133]
	v_cvt_pk_bf16_f32 v46, v46, v47
	v_cvt_pk_bf16_f32 v47, v56, v57
	v_lshl_add_u64 v[246:247], v[64:65], 0, v[244:245]
	global_store_dwordx4 v[246:247], v[44:47], off
	v_pk_mul_f32 v[22:23], v[22:23], v[134:135]
	v_pk_mul_f32 v[16:17], v[16:17], v[140:141]
	v_add_u32_e32 v44, 0x90, v164
	v_ashrrev_i32_e32 v45, 31, v44
	v_lshlrev_b64 v[44:45], 4, v[44:45]
	v_lshl_add_u64 v[44:45], s[0:1], 0, v[44:45]
	v_lshl_add_u64 v[44:45], v[44:45], 0, v[166:167]
	v_pk_mul_f32 v[46:47], v[50:51], v[142:143]
	v_pk_mul_f32 v[50:51], v[42:43], v[138:139]
	v_pk_mul_f32 v[42:43], v[40:41], v[136:137]
	v_cvt_pk_bf16_f32 v40, v48, v49
	v_cvt_pk_bf16_f32 v41, v46, v47
	v_pk_mul_f32 v[6:7], v[6:7], v[134:135]
	v_cvt_pk_bf16_f32 v42, v42, v43
	v_cvt_pk_bf16_f32 v43, v50, v51
	global_store_dwordx4 v[44:45], v[40:43], off
	v_pk_mul_f32 v[4:5], v[4:5], v[132:133]
	s_nop 0
	v_pk_mul_f32 v[40:41], v[30:31], v[130:131]
	v_pk_mul_f32 v[30:31], v[28:29], v[128:129]
	v_cvt_pk_bf16_f32 v28, v36, v37
	v_cvt_pk_bf16_f32 v29, v38, v39
	s_nop 0
	v_cvt_pk_bf16_f32 v30, v30, v31
	v_cvt_pk_bf16_f32 v31, v40, v41
	v_lshl_add_u64 v[246:247], v[44:45], 0, v[244:245]
	global_store_dwordx4 v[246:247], v[28:31], off
	s_nop 1
	v_add_u32_e32 v28, 0xa0, v164
	v_ashrrev_i32_e32 v29, 31, v28
	v_lshlrev_b64 v[28:29], 4, v[28:29]
	v_lshl_add_u64 v[28:29], s[0:1], 0, v[28:29]
	v_lshl_add_u64 v[28:29], v[28:29], 0, v[166:167]
	v_pk_mul_f32 v[30:31], v[34:35], v[142:143]
	v_pk_mul_f32 v[34:35], v[26:27], v[138:139]
	v_pk_mul_f32 v[26:27], v[24:25], v[136:137]
	v_cvt_pk_bf16_f32 v24, v32, v33
	v_cvt_pk_bf16_f32 v25, v30, v31
	s_nop 0
	v_cvt_pk_bf16_f32 v26, v26, v27
	v_cvt_pk_bf16_f32 v27, v34, v35
	global_store_dwordx4 v[28:29], v[24:27], off
	s_nop 1
	v_pk_mul_f32 v[24:25], v[14:15], v[130:131]
	v_pk_mul_f32 v[14:15], v[12:13], v[128:129]
	v_cvt_pk_bf16_f32 v12, v20, v21
	v_cvt_pk_bf16_f32 v13, v22, v23
	s_nop 0
	v_cvt_pk_bf16_f32 v14, v14, v15
	v_cvt_pk_bf16_f32 v15, v24, v25
	v_lshl_add_u64 v[246:247], v[28:29], 0, v[244:245]
	global_store_dwordx4 v[246:247], v[12:15], off
	s_nop 1
	v_add_u32_e32 v12, 0xb0, v164
	v_ashrrev_i32_e32 v13, 31, v12
	v_lshlrev_b64 v[12:13], 4, v[12:13]
	v_lshl_add_u64 v[12:13], s[0:1], 0, v[12:13]
	v_lshl_add_u64 v[12:13], v[12:13], 0, v[166:167]
	v_pk_mul_f32 v[14:15], v[18:19], v[142:143]
	v_pk_mul_f32 v[18:19], v[10:11], v[138:139]
	v_pk_mul_f32 v[10:11], v[8:9], v[136:137]
	v_cvt_pk_bf16_f32 v8, v16, v17
	v_cvt_pk_bf16_f32 v9, v14, v15
	s_nop 0
	v_cvt_pk_bf16_f32 v10, v10, v11
	v_cvt_pk_bf16_f32 v11, v18, v19
	global_store_dwordx4 v[12:13], v[8:11], off
	s_nop 1
	v_pk_mul_f32 v[8:9], v[2:3], v[130:131]
	v_pk_mul_f32 v[2:3], v[0:1], v[128:129]
	v_cvt_pk_bf16_f32 v0, v4, v5
	v_cvt_pk_bf16_f32 v1, v6, v7
	s_nop 0
	v_cvt_pk_bf16_f32 v2, v2, v3
	v_cvt_pk_bf16_f32 v3, v8, v9
	v_lshl_add_u64 v[246:247], v[12:13], 0, v[244:245]
	global_store_dwordx4 v[246:247], v[0:3], off
	s_cbranch_vccz .LBB0_137
	s_waitcnt vmcnt(0)
	s_cmpk_gt_u32 s3, 0xff
	s_cbranch_scc1 .LBB0_148
	s_barrier

; __device__ void phase_na(const Params& P, unsigned char* smem) {
;     ...
;     const bf16_t* Qp = (const bf16_t*)(P.ws + O_R2);
;     const bf16_t* Kp = (const bf16_t*)P.out;
;     const bf16_t* Vt = (const bf16_t*)((const unsigned char*)P.out + 128 * MiB);
;     const int h = blockIdx.x & 7, nbh = ((int)gridDim.x - h + 7) >> 3;
;     const float scale = 0.08838834764831845f;
;     for (int uu = ((int)blockIdx.x >> 3) * 8 + wid; uu < 2048; uu += nbh * 8) {
;         const int grow = uu >> 2, j = uu & 3;
;         int rows, r, tokbase;
;         if (grow < 256) { rows = 256; r = grow; tokbase = 0; } else { const int s = (grow - 256) >> 6; r = (grow - 256) & 63; rows = 64; tokbase = TP + s * 4096; }
;         const int rs = min(max(r - 4, 0), rows - 8);
;         const int q0 = j * 16, k0 = min(max(q0 - 8, 0), 32);
;         const size_t qtok = (size_t)tokbase + r * 64 + q0 + l15;
;         const bf16_t* qptr = Qp + qtok * 1024 + h * 128 + l4 * 8;
;     ...
;         mx = fmaxf(mx, __shfl_xor(mx, 16)); mx = fmaxf(mx, __shfl_xor(mx, 32));
;         float lsum = 0.f;
; #pragma unroll
;         for (int i = 0; i < 8; ++i)
; #pragma unroll
;             for (int a = 0; a < 2; ++a)
; #pragma unroll
;                 for (int jj = 0; jj < 4; ++jj) { const float p = __expf(st[i][a][jj] - mx); st[i][a][jj] = p; lsum += p; }
.LBB0_207:
	s_or_b64 exec, exec, s[0:1]
	s_and_b32 s0, s2, -8
	v_bfe_u32 v65, v144, 4, 2
	v_add_u32_e32 v84, s0, v146
	s_and_b32 s3, s2, 7
	v_lshlrev_b32_e32 v68, 3, v65
	s_movk_i32 s0, 0x800
	v_and_b32_e32 v64, 15, v144
	s_lshl_b32 s24, s3, 7
	v_lshlrev_b32_e32 v69, 2, v65
	v_cmp_gt_i32_e32 vcc, s0, v84
	v_lshlrev_b32_e32 v66, 1, v68
	s_waitcnt lgkmcnt(0)
	s_barrier
	s_and_saveexec_b64 s[4:5], vcc
	s_cbranch_execz .LBB0_338
	s_xor_b32 s8, s3, 7
	s_lshl_b32 s9, s24, 1
	v_lshlrev_b32_e32 v0, 1, v144
	s_add_u32 s0, s88, s9
	v_mov_b32_e32 v71, 0
	s_addc_u32 s1, s89, 0
	v_or_b32_sdwa v70, s24, v64 dst_sel:WORD_1 dst_unused:UNUSED_PAD src0_sel:DWORD src1_sel:DWORD
	v_mov_b32_e32 v67, v71
	v_and_b32_e32 v0, 24, v0
	v_and_or_b32 v85, v144, 3, v0
	v_lshl_add_u64 v[74:75], s[0:1], 0, v[66:67]
	v_lshl_add_u64 v[0:1], s[88:89], 0, v[70:71]
	s_mov_b64 s[0:1], 0x8000000
	v_lshl_add_u64 v[76:77], v[0:1], 0, s[0:1]
	v_lshrrev_b32_e32 v0, 12, v70
	v_mov_b32_e32 v1, 0
	v_lshl_add_u64 v[0:1], s[88:89], 0, v[0:1]
	v_lshl_add_u64 v[76:77], v[0:1], 0, s[0:1]
	v_mbcnt_lo_u32_b32 v0, -1, 0
	v_mbcnt_hi_u32_b32 v0, -1, v0
	v_and_b32_e32 v2, 64, v0
	s_add_u32 s6, s40, s9
	v_xor_b32_e32 v1, 16, v0
	v_add_u32_e32 v2, 64, v2
	s_addc_u32 s7, s41, 0
	s_add_i32 s10, s94, s8
	v_cmp_lt_i32_e32 vcc, v1, v2
	s_add_u32 s8, s36, s9
	s_addc_u32 s9, s37, 0
	v_cndmask_b32_e32 v1, v0, v1, vcc
	v_lshlrev_b32_e32 v86, 2, v1
	v_xor_b32_e32 v1, 32, v0
	s_lshl_b32 s0, s2, 4
	v_cmp_lt_i32_e32 vcc, v1, v2
	s_and_b32 s0, s0, 0xffffff80
	s_mul_i32 s25, s3, 15
	v_lshlrev_b32_e32 v70, 1, v69
	v_cndmask_b32_e32 v0, v0, v1, vcc
	v_lshl_add_u32 v88, v146, 4, s0
	s_lshl_b32 s0, s10, 4
	v_lshl_add_u64 v[72:73], s[8:9], 0, v[66:67]
	s_add_i32 s25, s25, 7
	s_and_b32 s26, s10, -8
	v_lshl_add_u64 v[78:79], s[6:7], 0, v[70:71]
	v_lshlrev_b32_e32 v87, 2, v0
	s_and_b32 s27, s0, 0xffffff80
	s_mov_b64 s[6:7], 0
	s_movk_i32 s42, 0x100
	v_mov_b32_e32 v89, 0xf8
	s_movk_i32 s43, 0x2000
	s_movk_i32 s44, 0x7c
	s_mov_b32 s45, 0xf149f2ca
	s_mov_b32 s46, 0x28000
	s_mov_b32 s47, 0x50000
	s_mov_b32 s48, 0x78000
	s_mov_b32 s49, 0xa0000
	s_mov_b32 s50, 0xc8000
	s_mov_b32 s51, 0xf0000
	s_mov_b32 s56, 0x118000
	s_movk_i32 s57, 0x7ff
	s_branch .LBB0_210
.LBB0_209:
	s_or_b64 exec, exec, s[8:9]
	v_max3_f32 v0, v90, s45, v83
	v_max3_f32 v0, v0, v61, v60
	v_max3_f32 v0, v0, v63, v62
	v_max3_f32 v0, v0, v57, v56
	v_max3_f32 v0, v0, v59, v58
	v_max3_f32 v0, v0, v53, v52
	v_max3_f32 v0, v0, v55, v54
	v_max3_f32 v0, v0, v49, v48
	v_max3_f32 v0, v0, v51, v50
	v_max3_f32 v0, v0, v45, v44
	v_max3_f32 v0, v0, v47, v46
	v_max3_f32 v0, v0, v41, v40
	v_max3_f32 v0, v0, v43, v42
	v_max3_f32 v0, v0, v102, v100
	v_max3_f32 v0, v0, v37, v36
	v_max3_f32 v0, v0, v33, v32
	v_max3_f32 v0, v0, v35, v34
	v_max3_f32 v0, v0, v29, v28
	v_max3_f32 v0, v0, v31, v30
	v_max3_f32 v0, v0, v25, v24
	v_max3_f32 v0, v0, v27, v26
	v_max3_f32 v0, v0, v38, v20
	v_max3_f32 v0, v0, v22, v21
	v_max3_f32 v0, v0, v23, v16
	v_max3_f32 v0, v0, v19, v17
	v_max3_f32 v0, v0, v39, v18
	v_max3_f32 v0, v0, v103, v101
	v_max3_f32 v0, v0, v106, v104
	v_max3_f32 v0, v0, v107, v105
	v_max3_f32 v0, v0, v108, v92
	v_max3_f32 v0, v0, v94, v93
	v_max3_f32 v0, v0, v96, v95
	ds_bpermute_b32 v1, v86, v0
	v_add_u32_e32 v84, s26, v84
	v_add_u32_e32 v88, s27, v88
	s_waitcnt lgkmcnt(0)
	v_max_f32_e32 v1, v1, v1
	v_max_f32_e32 v0, v0, v1
	ds_bpermute_b32 v1, v87, v0
	s_waitcnt lgkmcnt(0)
	v_max_f32_e32 v1, v1, v1
	v_max_f32_e32 v91, v0, v1
	v_sub_f32_e32 v0, v90, v91
	v_mul_f32_e32 v0, 0x3fb8aa3b, v0
	v_exp_f32_e32 v90, v0
	v_sub_f32_e32 v0, v63, v91
	v_mul_f32_e32 v0, 0x3fb8aa3b, v0
	v_exp_f32_e32 v63, v0
	v_sub_f32_e32 v0, v62, v91
	v_mul_f32_e32 v0, 0x3fb8aa3b, v0
	v_exp_f32_e32 v62, v0
	v_sub_f32_e32 v0, v57, v91
	v_mul_f32_e32 v0, 0x3fb8aa3b, v0
	v_exp_f32_e32 v57, v0
	v_sub_f32_e32 v0, v56, v91
	v_mul_f32_e32 v0, 0x3fb8aa3b, v0
	v_exp_f32_e32 v56, v0
	v_sub_f32_e32 v0, v59, v91
	v_mul_f32_e32 v0, 0x3fb8aa3b, v0
	v_exp_f32_e32 v59, v0
	v_sub_f32_e32 v0, v58, v91
	v_mul_f32_e32 v0, 0x3fb8aa3b, v0
	v_exp_f32_e32 v58, v0
	v_sub_f32_e32 v0, v53, v91
	v_mul_f32_e32 v0, 0x3fb8aa3b, v0
	v_exp_f32_e32 v53, v0
	v_sub_f32_e32 v0, v52, v91
	v_mul_f32_e32 v0, 0x3fb8aa3b, v0
	v_exp_f32_e32 v52, v0
	v_sub_f32_e32 v0, v55, v91
	v_mul_f32_e32 v0, 0x3fb8aa3b, v0
	v_exp_f32_e32 v55, v0
	v_sub_f32_e32 v0, v54, v91
	v_mul_f32_e32 v0, 0x3fb8aa3b, v0
	v_exp_f32_e32 v54, v0
	v_sub_f32_e32 v0, v49, v91
	v_mul_f32_e32 v0, 0x3fb8aa3b, v0
	v_exp_f32_e32 v49, v0
	v_sub_f32_e32 v0, v48, v91
	v_mul_f32_e32 v0, 0x3fb8aa3b, v0
	v_exp_f32_e32 v48, v0
	v_sub_f32_e32 v0, v51, v91
	v_mul_f32_e32 v0, 0x3fb8aa3b, v0
	v_exp_f32_e32 v51, v0
	v_sub_f32_e32 v0, v50, v91
	v_mul_f32_e32 v0, 0x3fb8aa3b, v0
	v_exp_f32_e32 v50, v0
	v_sub_f32_e32 v0, v45, v91
	v_mul_f32_e32 v0, 0x3fb8aa3b, v0
	v_exp_f32_e32 v45, v0
	v_sub_f32_e32 v0, v44, v91
	v_mul_f32_e32 v0, 0x3fb8aa3b, v0
	v_exp_f32_e32 v44, v0
	v_sub_f32_e32 v0, v47, v91
	v_mul_f32_e32 v0, 0x3fb8aa3b, v0
	v_exp_f32_e32 v47, v0
	v_sub_f32_e32 v0, v46, v91
	v_mul_f32_e32 v0, 0x3fb8aa3b, v0
	v_exp_f32_e32 v46, v0
	v_sub_f32_e32 v0, v41, v91
	v_mul_f32_e32 v0, 0x3fb8aa3b, v0
	v_exp_f32_e32 v41, v0
	v_sub_f32_e32 v0, v40, v91
	v_mul_f32_e32 v0, 0x3fb8aa3b, v0
	v_exp_f32_e32 v40, v0
	v_sub_f32_e32 v0, v43, v91
	v_mul_f32_e32 v0, 0x3fb8aa3b, v0
	v_exp_f32_e32 v43, v0
	v_sub_f32_e32 v0, v42, v91
	v_mul_f32_e32 v0, 0x3fb8aa3b, v0
	v_exp_f32_e32 v42, v0
	v_sub_f32_e32 v0, v102, v91
	v_mul_f32_e32 v0, 0x3fb8aa3b, v0
	v_sub_f32_e32 v1, v83, v91
	v_exp_f32_e32 v97, v0
	v_sub_f32_e32 v0, v100, v91
	v_mul_f32_e32 v1, 0x3fb8aa3b, v1
	v_mul_f32_e32 v0, 0x3fb8aa3b, v0
	v_exp_f32_e32 v83, v1
; __device__ __forceinline__ uint2 pk4(f32x4 v) { return make_uint2(cvt_pk_bf16(v[0], v[1]), cvt_pk_bf16(v[2], v[3])); }
; __device__ __forceinline__ f32x4 mfma16(bf16x8 a, bf16x8 b, f32x4 c) { return __builtin_amdgcn_mfma_f32_16x16x32_bf16(a, b, c, 0, 0, 0); }
; __device__ void phase_na(const Params& P, unsigned char* smem) {
;     ...
;         for (int i = 0; i < 8; ++i) {
;             const uint2 p0 = pk4(st[i][0]), p1 = pk4(st[i][1]);
;             const uint4 pw = make_uint4(p0.x, p0.y, p1.x, p1.y);
;             const bf16x8 pf = __builtin_bit_cast(bf16x8, pw);
;             const bf16_t* vbase = Vt + (size_t)(h * 128 + l15) * T + tokbase + (rs + i) * 64 + k0 + l4 * 8;
; #pragma unroll
;             for (int dt = 0; dt < 8; ++dt) {
;                 const bf16_t* vp = vbase + (size_t)dt * 16 * T;
;                 const uint4 vw = *(const uint4*)vp;
;                 o[dt] = mfma16(__builtin_bit_cast(bf16x8, vw), pf, o[dt]);
;             }
;         }
	v_exp_f32_e32 v98, v0
	v_lshlrev_b64 v[0:1], 1, v[70:71]
	v_lshlrev_b32_e32 v70, 1, v67
	v_lshl_add_u64 v[0:1], v[0:1], 0, v[70:71]
	v_mov_b32_e32 v67, v71
	v_sub_f32_e32 v2, v61, v91
	v_lshl_add_u64 v[0:1], v[0:1], 0, v[66:67]
	v_lshlrev_b32_e32 v70, 1, v82
	v_sub_f32_e32 v3, v60, v91
	v_mul_f32_e32 v2, 0x3fb8aa3b, v2
	v_lshl_add_u64 v[0:1], v[0:1], 0, v[70:71]
	v_mul_u32_u24_e32 v0, 0x500, v0
	v_mov_b32_e32 v1, 0
	v_lshl_add_u64 v[0:1], v[0:1], 0, v[76:77]
	v_mul_f32_e32 v3, 0x3fb8aa3b, v3
	v_exp_f32_e32 v61, v2
	v_add_co_u32_e32 v2, vcc, s46, v0
	v_exp_f32_e32 v60, v3
	s_nop 0
	v_addc_co_u32_e32 v3, vcc, 0, v1, vcc
	v_add_co_u32_e32 v6, vcc, s47, v0
	v_cvt_pk_bf16_f32 v110, v90, v83
	v_cvt_pk_bf16_f32 v111, v61, v60
	v_cvt_pk_bf16_f32 v112, v63, v62
	v_cvt_pk_bf16_f32 v113, v57, v56
	s_nop 1
	v_addc_co_u32_e32 v7, vcc, 0, v1, vcc
	v_add_co_u32_e32 v10, vcc, s48, v0
	global_load_dwordx4 v[114:117], v[0:1], off
	global_load_dwordx4 v[118:121], v[0:1], off offset:256
	v_addc_co_u32_e32 v11, vcc, 0, v1, vcc
	v_add_co_u32_e32 v14, vcc, s49, v0
	global_load_dwordx4 v[126:129], v[0:1], off offset:768
	s_nop 0
	v_addc_co_u32_e32 v15, vcc, 0, v1, vcc
	v_add_co_u32_e32 v8, vcc, s50, v0
	global_load_dwordx4 v[130:133], v[0:1], off offset:1024
	s_nop 0
	v_addc_co_u32_e32 v9, vcc, 0, v1, vcc
	global_load_dwordx4 v[134:137], v[0:1], off offset:1280
	global_load_dwordx4 v[122:125], v[0:1], off offset:512
	v_add_co_u32_e32 v12, vcc, s51, v0
	v_sub_f32_e32 v32, v32, v91
	s_nop 0
	v_addc_co_u32_e32 v13, vcc, 0, v1, vcc
	v_mul_f32_e32 v32, 0x3fb8aa3b, v32
	v_add_co_u32_e32 v4, vcc, s56, v0
	v_sub_f32_e32 v36, v36, v91
	v_sub_f32_e32 v33, v33, v91
	v_exp_f32_e32 v99, v32
	v_sub_f32_e32 v32, v35, v91
	v_addc_co_u32_e32 v5, vcc, 0, v1, vcc
	v_mul_f32_e32 v36, 0x3fb8aa3b, v36
	v_mul_f32_e32 v33, 0x3fb8aa3b, v33
	v_mul_f32_e32 v32, 0x3fb8aa3b, v32
	global_load_dwordx4 v[138:141], v[0:1], off offset:1536
	global_load_dwordx4 v[148:151], v[0:1], off offset:1792
	v_cvt_pk_bf16_f32 v152, v59, v58
	v_cvt_pk_bf16_f32 v153, v53, v52
	v_cvt_pk_bf16_f32 v154, v55, v54
	v_cvt_pk_bf16_f32 v155, v49, v48
	global_load_dwordx4 v[156:159], v[2:3], off
	global_load_dwordx4 v[160:163], v[2:3], off offset:256
	v_exp_f32_e32 v70, v36
	global_load_dwordx4 v[164:167], v[2:3], off offset:512
	global_load_dwordx4 v[180:183], v[2:3], off offset:1792
	v_exp_f32_e32 v82, v33
	global_load_dwordx4 v[168:171], v[2:3], off offset:768
	v_exp_f32_e32 v142, v32
	v_sub_f32_e32 v36, v34, v91
	global_load_dwordx4 v[32:35], v[2:3], off offset:1280
	v_sub_f32_e32 v28, v28, v91
	v_mul_f32_e32 v28, 0x3fb8aa3b, v28
	v_sub_f32_e32 v29, v29, v91
	v_exp_f32_e32 v147, v28
	v_sub_f32_e32 v28, v31, v91
	v_mul_f32_e32 v36, 0x3fb8aa3b, v36
	v_mul_f32_e32 v29, 0x3fb8aa3b, v29
	v_mul_f32_e32 v28, 0x3fb8aa3b, v28
	global_load_dwordx4 v[172:175], v[2:3], off offset:1024
	global_load_dwordx4 v[176:179], v[2:3], off offset:1536
	v_exp_f32_e32 v143, v36
	v_exp_f32_e32 v145, v29
	v_cvt_pk_bf16_f32 v184, v51, v50
	v_cvt_pk_bf16_f32 v185, v45, v44
	v_cvt_pk_bf16_f32 v186, v47, v46
	v_cvt_pk_bf16_f32 v187, v41, v40
	global_load_dwordx4 v[188:191], v[6:7], off
	v_exp_f32_e32 v224, v28
	v_sub_f32_e32 v36, v30, v91
	global_load_dwordx4 v[28:31], v[6:7], off offset:256
	global_load_dwordx4 v[192:195], v[6:7], off offset:512
	global_load_dwordx4 v[196:199], v[6:7], off offset:768
	global_load_dwordx4 v[204:207], v[6:7], off offset:1280
	v_sub_f32_e32 v24, v24, v91
	v_mul_f32_e32 v24, 0x3fb8aa3b, v24
	v_exp_f32_e32 v227, v24
	v_sub_f32_e32 v24, v27, v91
	v_mul_f32_e32 v24, 0x3fb8aa3b, v24
	v_sub_f32_e32 v25, v25, v91
	v_exp_f32_e32 v228, v24
	v_sub_f32_e32 v24, v26, v91
	v_mul_f32_e32 v25, 0x3fb8aa3b, v25
	v_mul_f32_e32 v24, 0x3fb8aa3b, v24
	v_exp_f32_e32 v226, v25
	global_load_dwordx4 v[200:203], v[6:7], off offset:1024
	global_load_dwordx4 v[208:211], v[6:7], off offset:1536
	v_exp_f32_e32 v229, v24
	s_waitcnt vmcnt(19)
	v_mfma_f32_16x16x32_bf16 v[24:27], v[130:133], v[110:113], 0
	v_sub_f32_e32 v20, v20, v91
	v_mul_f32_e32 v20, 0x3fb8aa3b, v20
	v_sub_f32_e32 v37, v37, v91
	s_waitcnt vmcnt(18)
	v_mfma_f32_16x16x32_bf16 v[130:133], v[134:137], v[110:113], 0
	global_load_dwordx4 v[134:137], v[6:7], off offset:1792
	v_exp_f32_e32 v231, v20
	v_sub_f32_e32 v20, v22, v91
	v_mfma_f32_16x16x32_bf16 v[114:117], v[114:117], v[110:113], 0
	v_sub_f32_e32 v16, v16, v91
	v_mul_f32_e32 v37, 0x3fb8aa3b, v37
	v_mul_f32_e32 v36, 0x3fb8aa3b, v36
	v_mfma_f32_16x16x32_bf16 v[118:121], v[118:121], v[110:113], 0
	v_mul_f32_e32 v20, 0x3fb8aa3b, v20
	v_mul_f32_e32 v16, 0x3fb8aa3b, v16
	v_exp_f32_e32 v67, v37
	s_waitcnt vmcnt(18)
	v_mfma_f32_16x16x32_bf16 v[122:125], v[122:125], v[110:113], 0
	v_exp_f32_e32 v225, v36
	v_sub_f32_e32 v36, v38, v91
	v_cvt_pk_bf16_f32 v212, v43, v42
	v_mfma_f32_16x16x32_bf16 v[126:129], v[126:129], v[110:113], 0
	v_cvt_pk_bf16_f32 v213, v97, v98
	v_cvt_pk_bf16_f32 v214, v67, v70
	v_cvt_pk_bf16_f32 v215, v82, v99
	global_load_dwordx4 v[216:219], v[10:11], off
	global_load_dwordx4 v[220:223], v[10:11], off offset:256
	v_exp_f32_e32 v232, v20
	v_sub_f32_e32 v20, v21, v91
	v_exp_f32_e32 v235, v16
	v_sub_f32_e32 v16, v19, v91
	v_mul_f32_e32 v36, 0x3fb8aa3b, v36
	v_mul_f32_e32 v20, 0x3fb8aa3b, v20
	v_mul_f32_e32 v16, 0x3fb8aa3b, v16
	v_exp_f32_e32 v230, v36
	s_waitcnt vmcnt(19)
	v_mfma_f32_16x16x32_bf16 v[138:141], v[138:141], v[110:113], 0
	v_exp_f32_e32 v233, v20
	v_sub_f32_e32 v36, v23, v91
	global_load_dwordx4 v[20:23], v[10:11], off offset:1280
	s_waitcnt vmcnt(19)
	v_mfma_f32_16x16x32_bf16 v[110:113], v[148:151], v[110:113], 0
	global_load_dwordx4 v[148:151], v[10:11], off offset:512
	v_exp_f32_e32 v236, v16
	v_sub_f32_e32 v16, v17, v91
	s_waitcnt vmcnt(19)
; __device__ __forceinline__ uint2 pk4(f32x4 v) { return make_uint2(cvt_pk_bf16(v[0], v[1]), cvt_pk_bf16(v[2], v[3])); }
; __device__ __forceinline__ f32x4 mfma16(bf16x8 a, bf16x8 b, f32x4 c) { return __builtin_amdgcn_mfma_f32_16x16x32_bf16(a, b, c, 0, 0, 0); }
; __device__ void phase_na(const Params& P, unsigned char* smem) {
;     ...
;         for (int i = 0; i < 8; ++i) {
;             const uint2 p0 = pk4(st[i][0]), p1 = pk4(st[i][1]);
;             const uint4 pw = make_uint4(p0.x, p0.y, p1.x, p1.y);
;             const bf16x8 pf = __builtin_bit_cast(bf16x8, pw);
;             const bf16_t* vbase = Vt + (size_t)(h * 128 + l15) * T + tokbase + (rs + i) * 64 + k0 + l4 * 8;
; #pragma unroll
;             for (int dt = 0; dt < 8; ++dt) {
;                 const bf16_t* vp = vbase + (size_t)dt * 16 * T;
;                 const uint4 vw = *(const uint4*)vp;
;                 o[dt] = mfma16(__builtin_bit_cast(bf16x8, vw), pf, o[dt]);
;             }
;         }
	v_mfma_f32_16x16x32_bf16 v[114:117], v[156:159], v[152:155], v[114:117]
	global_load_dwordx4 v[156:159], v[10:11], off offset:768
	v_mul_f32_e32 v16, 0x3fb8aa3b, v16
	v_exp_f32_e32 v237, v16
	s_waitcnt vmcnt(19)
	v_mfma_f32_16x16x32_bf16 v[118:121], v[160:163], v[152:155], v[118:121]
	global_load_dwordx4 v[160:163], v[10:11], off offset:1024
	v_sub_f32_e32 v16, v39, v91
	v_mul_f32_e32 v36, 0x3fb8aa3b, v36
	s_waitcnt vmcnt(19)
	v_mfma_f32_16x16x32_bf16 v[122:125], v[164:167], v[152:155], v[122:125]
	global_load_dwordx4 v[164:167], v[10:11], off offset:1536
	v_mul_f32_e32 v16, 0x3fb8aa3b, v16
	v_exp_f32_e32 v234, v36
	s_waitcnt vmcnt(18)
	v_mfma_f32_16x16x32_bf16 v[126:129], v[168:171], v[152:155], v[126:129]
	v_exp_f32_e32 v238, v16
	v_sub_f32_e32 v100, v18, v91
	v_mul_f32_e32 v100, 0x3fb8aa3b, v100
	s_waitcnt vmcnt(17)
	v_mfma_f32_16x16x32_bf16 v[32:35], v[32:35], v[152:155], v[130:133]
	v_exp_f32_e32 v239, v100
	v_sub_f32_e32 v100, v103, v91
	v_mul_f32_e32 v100, 0x3fb8aa3b, v100
	global_load_dwordx4 v[130:133], v[10:11], off offset:1792
	s_waitcnt vmcnt(17)
	v_mfma_f32_16x16x32_bf16 v[24:27], v[172:175], v[152:155], v[24:27]
	v_cvt_pk_bf16_f32 v168, v142, v143
	v_cvt_pk_bf16_f32 v169, v145, v147
	v_cvt_pk_bf16_f32 v170, v224, v225
	v_cvt_pk_bf16_f32 v171, v226, v227
	global_load_dwordx4 v[172:175], v[14:15], off
	s_waitcnt vmcnt(17)
	v_mfma_f32_16x16x32_bf16 v[138:141], v[176:179], v[152:155], v[138:141]
	global_load_dwordx4 v[176:179], v[14:15], off offset:256
	global_load_dwordx4 v[36:39], v[14:15], off offset:768
	v_exp_f32_e32 v240, v100
	v_mfma_f32_16x16x32_bf16 v[110:113], v[180:183], v[152:155], v[110:113]
	global_load_dwordx4 v[152:155], v[14:15], off offset:512
	global_load_dwordx4 v[180:183], v[14:15], off offset:1792
	v_sub_f32_e32 v100, v101, v91
	s_waitcnt vmcnt(19)
	v_mfma_f32_16x16x32_bf16 v[28:31], v[28:31], v[184:187], v[118:121]
	v_mul_f32_e32 v100, 0x3fb8aa3b, v100
	v_exp_f32_e32 v241, v100
	global_load_dwordx4 v[100:103], v[14:15], off offset:1536
	global_load_dwordx4 v[118:121], v[14:15], off offset:1024
	s_waitcnt vmcnt(20)
	v_mfma_f32_16x16x32_bf16 v[16:19], v[192:195], v[184:187], v[122:125]
	v_sub_f32_e32 v92, v92, v91
	v_mul_f32_e32 v92, 0x3fb8aa3b, v92
	v_sub_f32_e32 v109, v105, v91
	s_waitcnt vmcnt(19)
	v_mfma_f32_16x16x32_bf16 v[122:125], v[196:199], v[184:187], v[126:129]
	v_sub_f32_e32 v108, v108, v91
	v_sub_f32_e32 v104, v104, v91
	v_mul_f32_e32 v109, 0x3fb8aa3b, v109
	global_load_dwordx4 v[126:129], v[14:15], off offset:1280
	v_mfma_f32_16x16x32_bf16 v[114:117], v[188:191], v[184:187], v[114:117]
	v_cvt_pk_bf16_f32 v188, v228, v229
	v_cvt_pk_bf16_f32 v189, v230, v231
	v_cvt_pk_bf16_f32 v190, v232, v233
	s_waitcnt vmcnt(18)
	v_mfma_f32_16x16x32_bf16 v[24:27], v[200:203], v[184:187], v[24:27]
	v_cvt_pk_bf16_f32 v191, v234, v235
	v_mul_f32_e32 v108, 0x3fb8aa3b, v108
	v_mul_f32_e32 v104, 0x3fb8aa3b, v104
	v_mfma_f32_16x16x32_bf16 v[32:35], v[204:207], v[184:187], v[32:35]
	v_sub_f32_e32 v106, v106, v91
	v_mul_f32_e32 v106, 0x3fb8aa3b, v106
	global_load_dwordx4 v[192:195], v[8:9], off
	s_waitcnt vmcnt(18)
	v_mfma_f32_16x16x32_bf16 v[138:141], v[208:211], v[184:187], v[138:141]
	v_exp_f32_e32 v211, v109
	v_exp_f32_e32 v209, v104
	v_sub_f32_e32 v104, v107, v91
	s_waitcnt vmcnt(17)
	v_mfma_f32_16x16x32_bf16 v[110:113], v[134:137], v[184:187], v[110:113]
	global_load_dwordx4 v[184:187], v[8:9], off offset:512
	global_load_dwordx4 v[134:137], v[8:9], off offset:256
	v_mul_f32_e32 v104, 0x3fb8aa3b, v104
	s_waitcnt vmcnt(18)
	v_mfma_f32_16x16x32_bf16 v[114:117], v[216:219], v[212:215], v[114:117]
	v_exp_f32_e32 v217, v92
	v_sub_f32_e32 v92, v94, v91
	v_mul_f32_e32 v92, 0x3fb8aa3b, v92
	s_waitcnt vmcnt(17)
	v_mfma_f32_16x16x32_bf16 v[28:31], v[220:223], v[212:215], v[28:31]
	v_exp_f32_e32 v216, v108
	v_exp_f32_e32 v208, v106
	v_exp_f32_e32 v210, v104
	s_waitcnt vmcnt(15)
	v_mfma_f32_16x16x32_bf16 v[16:19], v[148:151], v[212:215], v[16:19]
	global_load_dwordx4 v[104:107], v[8:9], off offset:768
	global_load_dwordx4 v[148:151], v[8:9], off offset:1024
	s_waitcnt vmcnt(16)
	v_mfma_f32_16x16x32_bf16 v[122:125], v[156:159], v[212:215], v[122:125]
	global_load_dwordx4 v[156:159], v[8:9], off offset:1280
	s_waitcnt vmcnt(16)
	v_mfma_f32_16x16x32_bf16 v[24:27], v[160:163], v[212:215], v[24:27]
	global_load_dwordx4 v[160:163], v[8:9], off offset:1536
	v_mfma_f32_16x16x32_bf16 v[20:23], v[20:23], v[212:215], v[32:35]
	s_waitcnt vmcnt(16)
	v_mfma_f32_16x16x32_bf16 v[138:141], v[164:167], v[212:215], v[138:141]
	s_nop 0
	global_load_dwordx4 v[32:35], v[8:9], off offset:1792
	v_cvt_pk_bf16_f32 v196, v236, v237
	v_cvt_pk_bf16_f32 v197, v238, v239
	s_waitcnt vmcnt(16)
	v_mfma_f32_16x16x32_bf16 v[108:111], v[130:133], v[212:215], v[110:113]
	v_exp_f32_e32 v212, v92
	v_sub_f32_e32 v92, v93, v91
	v_mul_f32_e32 v92, 0x3fb8aa3b, v92
	v_exp_f32_e32 v213, v92
	v_sub_f32_e32 v92, v96, v91
	v_sub_f32_e32 v91, v95, v91
	v_mul_f32_e32 v92, 0x3fb8aa3b, v92
	v_mul_f32_e32 v91, 0x3fb8aa3b, v91
	v_cvt_pk_bf16_f32 v198, v240, v241
	v_cvt_pk_bf16_f32 v199, v208, v209
	global_load_dwordx4 v[200:203], v[12:13], off
	global_load_dwordx4 v[164:167], v[12:13], off offset:256
	global_load_dwordx4 v[130:133], v[12:13], off offset:512
	s_waitcnt vmcnt(18)
	v_mfma_f32_16x16x32_bf16 v[112:115], v[172:175], v[168:171], v[114:117]
	global_load_dwordx4 v[172:175], v[12:13], off offset:768
	v_exp_f32_e32 v96, v92
	global_load_dwordx4 v[92:95], v[12:13], off offset:1536
	s_waitcnt vmcnt(19)
	v_mfma_f32_16x16x32_bf16 v[28:31], v[176:179], v[168:171], v[28:31]
	global_load_dwordx4 v[176:179], v[12:13], off offset:1024
	v_exp_f32_e32 v91, v91
	s_waitcnt vmcnt(18)
; __device__ __forceinline__ uint2 pk4(f32x4 v) { return make_uint2(cvt_pk_bf16(v[0], v[1]), cvt_pk_bf16(v[2], v[3])); }
; __device__ __forceinline__ f32x4 mfma16(bf16x8 a, bf16x8 b, f32x4 c) { return __builtin_amdgcn_mfma_f32_16x16x32_bf16(a, b, c, 0, 0, 0); }
; __device__ void phase_na(const Params& P, unsigned char* smem) {
;     ...
;         float lsum = 0.f;
; #pragma unroll
;         for (int i = 0; i < 8; ++i)
; #pragma unroll
;             for (int a = 0; a < 2; ++a)
; #pragma unroll
;                 for (int jj = 0; jj < 4; ++jj) { const float p = __expf(st[i][a][jj] - mx); st[i][a][jj] = p; lsum += p; }
;         lsum += __shfl_xor(lsum, 16); lsum += __shfl_xor(lsum, 32);
;     ...
;         for (int i = 0; i < 8; ++i) {
;             const uint2 p0 = pk4(st[i][0]), p1 = pk4(st[i][1]);
;             const uint4 pw = make_uint4(p0.x, p0.y, p1.x, p1.y);
;             const bf16x8 pf = __builtin_bit_cast(bf16x8, pw);
;             const bf16_t* vbase = Vt + (size_t)(h * 128 + l15) * T + tokbase + (rs + i) * 64 + k0 + l4 * 8;
; #pragma unroll
;             for (int dt = 0; dt < 8; ++dt) {
;                 const bf16_t* vp = vbase + (size_t)dt * 16 * T;
;                 const uint4 vw = *(const uint4*)vp;
;                 o[dt] = mfma16(__builtin_bit_cast(bf16x8, vw), pf, o[dt]);
;             }
;         }
	v_mfma_f32_16x16x32_bf16 v[16:19], v[152:155], v[168:171], v[16:19]
	global_load_dwordx4 v[152:155], v[12:13], off offset:1280
	v_mfma_f32_16x16x32_bf16 v[36:39], v[36:39], v[168:171], v[122:125]
	s_waitcnt vmcnt(16)
	v_mfma_f32_16x16x32_bf16 v[24:27], v[118:121], v[168:171], v[24:27]
	global_load_dwordx4 v[116:119], v[12:13], off offset:1792
	v_cvt_pk_bf16_f32 v120, v210, v211
	v_cvt_pk_bf16_f32 v121, v216, v217
	v_cvt_pk_bf16_f32 v122, v212, v213
	v_cvt_pk_bf16_f32 v123, v96, v91
	global_load_dwordx4 v[204:207], v[4:5], off
	s_waitcnt vmcnt(17)
	v_mfma_f32_16x16x32_bf16 v[20:23], v[126:129], v[168:171], v[20:23]
	global_load_dwordx4 v[0:3], v[4:5], off offset:256
	s_nop 0
	global_load_dwordx4 v[124:127], v[4:5], off offset:512
	v_add_f32_e32 v6, 0, v90
	v_add_f32_e32 v6, v83, v6
	v_add_f32_e32 v6, v61, v6
	v_add_f32_e32 v6, v60, v6
	v_add_f32_e32 v6, v63, v6
	v_add_f32_e32 v6, v62, v6
	v_add_f32_e32 v6, v57, v6
	v_mfma_f32_16x16x32_bf16 v[100:103], v[100:103], v[168:171], v[138:141]
	s_nop 2
	global_load_dwordx4 v[138:141], v[4:5], off offset:768
	v_mfma_f32_16x16x32_bf16 v[108:111], v[180:183], v[168:171], v[108:111]
	global_load_dwordx4 v[168:171], v[4:5], off offset:1024
	v_add_f32_e32 v10, v56, v6
	global_load_dwordx4 v[6:9], v[4:5], off offset:1280
	v_add_f32_e32 v10, v59, v10
	v_add_f32_e32 v10, v58, v10
	v_add_f32_e32 v53, v53, v10
	s_waitcnt vmcnt(20)
	v_mfma_f32_16x16x32_bf16 v[14:17], v[184:187], v[188:191], v[16:19]
	global_load_dwordx4 v[10:13], v[4:5], off offset:1536
	s_nop 1
	v_add_f32_e32 v18, v52, v53
	v_add_f32_e32 v18, v55, v18
	v_add_f32_e32 v18, v54, v18
	global_load_dwordx4 v[52:55], v[4:5], off offset:1792
	v_add_f32_e32 v18, v49, v18
	v_add_f32_e32 v18, v48, v18
	v_add_f32_e32 v4, v51, v18
	v_add_f32_e32 v4, v50, v4
	v_add_f32_e32 v4, v45, v4
	v_add_f32_e32 v4, v44, v4
	v_add_f32_e32 v4, v47, v4
	v_add_f32_e32 v4, v46, v4
	v_add_f32_e32 v4, v41, v4
	v_add_f32_e32 v4, v40, v4
	v_add_f32_e32 v4, v43, v4
	v_add_f32_e32 v4, v42, v4
	v_add_f32_e32 v4, v97, v4
	v_add_f32_e32 v4, v98, v4
	v_add_f32_e32 v4, v67, v4
	v_add_f32_e32 v4, v70, v4
	v_add_f32_e32 v4, v82, v4
	v_add_f32_e32 v4, v99, v4
	v_add_f32_e32 v4, v142, v4
	v_add_f32_e32 v4, v143, v4
	v_add_f32_e32 v4, v145, v4
	v_add_f32_e32 v4, v147, v4
	v_add_f32_e32 v4, v224, v4
	v_add_f32_e32 v4, v225, v4
	v_add_f32_e32 v4, v226, v4
	v_add_f32_e32 v4, v227, v4
	v_add_f32_e32 v4, v228, v4
	v_add_f32_e32 v4, v229, v4
	v_add_f32_e32 v4, v230, v4
	v_add_f32_e32 v4, v231, v4
	v_add_f32_e32 v4, v232, v4
	v_add_f32_e32 v4, v233, v4
	v_add_f32_e32 v4, v234, v4
	v_add_f32_e32 v4, v235, v4
	v_add_f32_e32 v4, v236, v4
	v_add_f32_e32 v4, v237, v4
	v_add_f32_e32 v4, v238, v4
	v_add_f32_e32 v4, v239, v4
	v_add_f32_e32 v4, v240, v4
	v_add_f32_e32 v4, v241, v4
	v_add_f32_e32 v4, v208, v4
	v_add_f32_e32 v4, v209, v4
	v_add_f32_e32 v4, v210, v4
	v_add_f32_e32 v4, v211, v4
	v_add_f32_e32 v4, v216, v4
	v_add_f32_e32 v4, v217, v4
	v_add_f32_e32 v4, v212, v4
	s_waitcnt vmcnt(21)
	v_mfma_f32_16x16x32_bf16 v[28:31], v[134:137], v[188:191], v[28:31]
	v_add_f32_e32 v4, v213, v4
	v_add_f32_e32 v4, v96, v4
	v_add_f32_e32 v4, v91, v4
	s_waitcnt vmcnt(18)
	v_mfma_f32_16x16x32_bf16 v[18:21], v[156:159], v[188:191], v[20:23]
	ds_bpermute_b32 v5, v86, v4
	s_waitcnt vmcnt(14)
	v_mfma_f32_16x16x32_bf16 v[28:31], v[164:167], v[196:199], v[28:31]
	s_waitcnt vmcnt(9)
	v_mfma_f32_16x16x32_bf16 v[18:21], v[152:155], v[196:199], v[18:21]
	v_mfma_f32_16x16x32_bf16 v[36:39], v[104:107], v[188:191], v[36:39]
	s_waitcnt vmcnt(6)
	v_mfma_f32_16x16x32_bf16 v[0:3], v[0:3], v[120:123], v[28:31]
	s_waitcnt lgkmcnt(0)
	s_nop 1
	v_add_f32_e32 v30, v4, v5
	s_waitcnt vmcnt(2)
; __device__ __forceinline__ uint2 pk4(f32x4 v) { return make_uint2(cvt_pk_bf16(v[0], v[1]), cvt_pk_bf16(v[2], v[3])); }
; __device__ __forceinline__ f32x4 mfma16(bf16x8 a, bf16x8 b, f32x4 c) { return __builtin_amdgcn_mfma_f32_16x16x32_bf16(a, b, c, 0, 0, 0); }
; __device__ void phase_na(const Params& P, unsigned char* smem) {
;     ...
;                 o[dt] = mfma16(__builtin_bit_cast(bf16x8, vw), pf, o[dt]);
;             }
;         }
;         const float inv = 1.f / lsum;
;         bf16_t* optr = (bf16_t*)(P.ws + O_R3) + qtok * 1024 + h * 128 + l4 * 4;
; #pragma unroll
;         for (int dt = 0; dt < 8; ++dt) *(uint2*)(optr + dt * 16) = pk4(o[dt] * inv);
	v_mfma_f32_16x16x32_bf16 v[4:7], v[6:9], v[120:123], v[18:21]
	s_nop 2
	ds_bpermute_b32 v18, v87, v30
	v_mfma_f32_16x16x32_bf16 v[24:27], v[148:151], v[188:191], v[24:27]
	s_waitcnt lgkmcnt(0)
	v_add_f32_e32 v30, v30, v18
	v_mfma_f32_16x16x32_bf16 v[32:35], v[32:35], v[188:191], v[108:111]
	v_div_scale_f32 v31, s[0:1], v30, v30, 1.0
	v_mfma_f32_16x16x32_bf16 v[36:39], v[172:175], v[196:199], v[36:39]
	v_mfma_f32_16x16x32_bf16 v[112:115], v[192:195], v[188:191], v[112:115]
	v_mfma_f32_16x16x32_bf16 v[22:25], v[176:179], v[196:199], v[24:27]
	v_mfma_f32_16x16x32_bf16 v[32:35], v[116:119], v[196:199], v[32:35]
	v_mfma_f32_16x16x32_bf16 v[26:29], v[138:141], v[120:123], v[36:39]
	s_nop 3
	v_rcp_f32_e32 v36, v31
	v_mfma_f32_16x16x32_bf16 v[44:47], v[160:163], v[188:191], v[100:103]
	v_mfma_f32_16x16x32_bf16 v[40:43], v[200:203], v[196:199], v[112:115]
	s_waitcnt vmcnt(0)
	v_mfma_f32_16x16x32_bf16 v[18:21], v[52:55], v[120:123], v[32:35]
	s_nop 2
	v_fma_f32 v32, -v31, v36, 1.0
	v_mfma_f32_16x16x32_bf16 v[14:17], v[130:133], v[196:199], v[14:17]
	v_fmac_f32_e32 v36, v32, v36
	v_div_scale_f32 v32, vcc, 1.0, v30, 1.0
	v_mul_f32_e32 v33, v32, v36
	v_mfma_f32_16x16x32_bf16 v[44:47], v[92:95], v[196:199], v[44:47]
	v_fma_f32 v34, -v31, v33, v32
	v_fmac_f32_e32 v33, v34, v36
	v_fma_f32 v31, -v31, v33, v32
	v_mfma_f32_16x16x32_bf16 v[40:43], v[204:207], v[120:123], v[40:43]
	v_div_fmas_f32 v31, v31, v36, v33
	v_div_fixup_f32 v30, v31, v30, 1.0
	v_pk_mul_f32 v[2:3], v[30:31], v[2:3] op_sel_hi:[0,1]
	v_mfma_f32_16x16x32_bf16 v[14:17], v[124:127], v[120:123], v[14:17]
	v_mul_f32_e64 v0, v30, v0
	v_mul_f32_e64 v1, v30, v1
	s_nop 1
	v_pk_mul_f32 v[34:35], v[30:31], v[40:41] op_sel_hi:[0,1]
	v_pk_mul_f32 v[32:33], v[30:31], v[42:43] op_sel_hi:[0,1]
	v_mfma_f32_16x16x32_bf16 v[8:11], v[10:13], v[120:123], v[44:47]
	v_lshlrev_b64 v[12:13], 10, v[80:81]
	v_lshl_add_u64 v[12:13], v[12:13], 1, v[78:79]
	v_cvt_pk_bf16_f32 v34, v34, v35
	v_mfma_f32_16x16x32_bf16 v[22:25], v[168:171], v[120:123], v[22:25]
	v_cvt_pk_bf16_f32 v35, v32, v33
	global_store_dwordx2 v[12:13], v[34:35], off
	v_cvt_pk_bf16_f32 v0, v0, v1
	v_cvt_pk_bf16_f32 v1, v2, v3
	v_pk_mul_f32 v[2:3], v[30:31], v[14:15] op_sel_hi:[0,1]
	global_store_dwordx2 v[12:13], v[0:1], off offset:32
	v_pk_mul_f32 v[0:1], v[30:31], v[16:17] op_sel_hi:[0,1]
	v_cvt_pk_bf16_f32 v2, v2, v3
	v_cvt_pk_bf16_f32 v3, v0, v1
	global_store_dwordx2 v[12:13], v[2:3], off offset:64
	v_pk_mul_f32 v[2:3], v[30:31], v[26:27] op_sel_hi:[0,1]
	v_pk_mul_f32 v[0:1], v[30:31], v[28:29] op_sel_hi:[0,1]
	v_cvt_pk_bf16_f32 v2, v2, v3
	v_cvt_pk_bf16_f32 v3, v0, v1
	global_store_dwordx2 v[12:13], v[2:3], off offset:96
	v_pk_mul_f32 v[2:3], v[30:31], v[22:23] op_sel_hi:[0,1]
	v_pk_mul_f32 v[0:1], v[30:31], v[24:25] op_sel_hi:[0,1]
	v_cvt_pk_bf16_f32 v2, v2, v3
	v_cvt_pk_bf16_f32 v3, v0, v1
	global_store_dwordx2 v[12:13], v[2:3], off offset:128
	v_pk_mul_f32 v[2:3], v[30:31], v[4:5] op_sel_hi:[0,1]
	v_pk_mul_f32 v[0:1], v[30:31], v[6:7] op_sel_hi:[0,1]
	v_cvt_pk_bf16_f32 v2, v2, v3
	v_cvt_pk_bf16_f32 v3, v0, v1
	global_store_dwordx2 v[12:13], v[2:3], off offset:160
	v_pk_mul_f32 v[2:3], v[30:31], v[8:9] op_sel_hi:[0,1]
	v_pk_mul_f32 v[0:1], v[30:31], v[10:11] op_sel_hi:[0,1]
	v_cvt_pk_bf16_f32 v2, v2, v3
	v_cvt_pk_bf16_f32 v3, v0, v1
	v_cmp_lt_i32_e32 vcc, s57, v84
	global_store_dwordx2 v[12:13], v[2:3], off offset:192
	v_pk_mul_f32 v[2:3], v[30:31], v[18:19] op_sel_hi:[0,1]
	s_or_b64 s[6:7], vcc, s[6:7]
	v_pk_mul_f32 v[0:1], v[30:31], v[20:21] op_sel_hi:[0,1]
	v_cvt_pk_bf16_f32 v2, v2, v3
	v_cvt_pk_bf16_f32 v3, v0, v1
	global_store_dwordx2 v[12:13], v[2:3], off offset:224
	s_andn2_b64 exec, exec, s[6:7]
	s_cbranch_execz .LBB0_338
